# up GEMM: accumulator clears (127 v_mov per unit) dropped, first MFMA into each accumulator in the peeled iteration takes C=0
# baseline (speedup 1.0000x reference)
; #define PG8_STAGE(bufoff, gbase, voff) do { _Pragma("unroll") for (int _i = 0; _i < 2; ++_i) \
;         __builtin_amdgcn_global_load_lds((const unsigned*)((const char*)(gbase) + (voff)[_i]), (LAS unsigned*)(lds + (bufoff) + ldsw + _i * 8192), 16, 0, 0); } while (0)
; #define PG8_LDA(dst, b, h) do { _Pragma("unroll") for (int m = 0; m < 4; ++m) _Pragma("unroll") for (int k = 0; k < 2; ++k) dst[m][k] = *(const LAS bf16x8*)(lds + PG8_SA(b, h) + aoff + m * 2048 + k * 1024); } while (0)
; template <class Epi, int AMODE>
; __device__ __forceinline__ void gemm_phase(LAS unsigned char* lds, const Gemm g, const StaticOrder& S, const Epi& E, int stagger_us, int tid_in) {
;     ...
;     for (;;) {
;         const bool has_next = S.next(ui + 1, nxt);
;         const char* nA = has_next ? Abase + (size_t)nxt.pm * tstepA : cA; const char* nB = has_next ? (const char*)g.Bt + (size_t)nxt.pn * tstepB : cB;
;         for (int t = 0; t < nt; t += 2) {
;             const bool last = (t == nt - 2);
;             const char* a1 = cA + (size_t)(t + 1) * kstep;
;             const char* a2 = last ? nA : cA + (size_t)(t + 2) * kstep; const char* b2 = last ? nB : cB + (size_t)(t + 2) * kstep;
;             const char* a3 = a2 + kstep; const char* b3 = b2 + kstep;
;             PG8_LDB(B0, 0, 0); PG8_LDB(B1, 0, 1); PG8_SCHED; PG8_LDA(At, 0, 0); PG8_STAGE(PG8_SA(1, 1), a1 + hstepA, voffA);
;             PG8_WAIT_V(8); PG8_WAIT_L(0); PG8_BAR; PG8_MMA(0, 0, At, B0); PG8_MMA(0, 1, At, B1); PG8_BAR; PG8_SCHED;
;     __device__ __forceinline__ void operator()(f32x4 (&acc)[2][2][4][2], const Unit& u, int wr, int wc, int fr, int fq) const {
;     ...
;             const int tq = tok0 + 8 * fr; const int tA = tq < 0 ? 0 : (tq > TOK - 1 ? TOK - 1 : tq), tB = (tq + 7) > TOK - 1 ? TOK - 1 : (tq + 7);
;             const int bA = batch_of(tA), bB = batch_of(tB); const bool same = __all(bA == bB);
;             const float* bp0 = bias + 256 * u.pn + 32 * wc + 8 * fq;
;             f32x4 bvA[2][2]; float sq[8];
; #pragma unroll
;             for (int am = 0; am < 8; ++am) { int tok = tq + am; tok = tok < 0 ? 0 : (tok > TOK - 1 ? TOK - 1 : tok); sq[am] = LDG(float, ssq + tok); }
; #pragma unroll
;             for (int bj = 0; bj < 2; ++bj)
; #pragma unroll
;                 for (int n = 0; n < 2; ++n) bvA[bj][n] = LDG(f32x4, bp0 + (size_t)bA * (2 * DFF) + bj * HALF + 4 * n);
.LBB0_1298:
	s_ashr_i32 s47, s46, 31
	s_lshl_b64 s[6:7], s[46:47], 20
	s_add_u32 s96, s9, s6
	s_addc_u32 s97, s72, s7
	s_and_b64 s[6:7], s[42:43], exec
	s_cselect_b32 s27, s97, s5
	s_cselect_b32 s28, s96, s4
	s_add_u32 s29, s4, 0x100
	v_mov_b32_e32 v2, 0
	s_addc_u32 s30, s5, 0
	s_mov_b32 s31, -2
	s_mul_i32 s6, s26, 0xfc
	v_add_u32_e32 v222, s6, v197
	v_med3_i32 v240, v222, 0, v238
	v_add_u32_e32 v241, 0xffffe000, v240
	v_lshrrev_b32_e32 v241, 12, v241
	v_add_u32_e32 v241, 4, v241
	v_lshrrev_b32_e32 v242, 11, v240
	v_mov_b32_e32 v243, 0x2000
	v_cmp_gt_i32_e64 s[6:7], v243, v222
	s_nop 1
	v_cndmask_b32_e64 v241, v241, v242, s[6:7]
	s_lshl_b32 s6, s92, 8
	s_ashr_i32 s7, s6, 31
	v_lshl_add_u64 v[236:237], s[6:7], 2, v[184:185]
	v_mad_u64_u32 v[236:237], s[6:7], v241, s15, v[236:237]
	v_med3_i32 v224, v222, 0, v238
	v_lshlrev_b32_e32 v224, 2, v224
	global_load_dword v224, v224, s[56:57]
	v_add_u32_e32 v228, 1, v222
	v_med3_i32 v228, v228, 0, v238
	v_lshlrev_b32_e32 v228, 2, v228
	global_load_dword v228, v228, s[56:57]
	v_add_u32_e32 v231, 2, v222
	v_med3_i32 v231, v231, 0, v238
	v_lshlrev_b32_e32 v231, 2, v231
	global_load_dword v231, v231, s[56:57]
	v_add_u32_e32 v233, 3, v222
	v_med3_i32 v233, v233, 0, v238
	v_lshlrev_b32_e32 v233, 2, v233
	global_load_dword v233, v233, s[56:57]
	v_add_u32_e32 v234, 4, v222
	v_med3_i32 v234, v234, 0, v238
	v_lshlrev_b32_e32 v234, 2, v234
	global_load_dword v234, v234, s[56:57]
	v_add_u32_e32 v239, 5, v222
	v_med3_i32 v239, v239, 0, v238
	v_lshlrev_b32_e32 v239, 2, v239
	global_load_dword v239, v239, s[56:57]
	v_add_u32_e32 v252, 6, v222
	v_med3_i32 v252, v252, 0, v238
	v_lshlrev_b32_e32 v252, 2, v252
	global_load_dword v252, v252, s[56:57]
	v_add_u32_e32 v253, 7, v222
	v_med3_i32 v253, v253, 0, v238
	v_lshlrev_b32_e32 v253, 2, v253
	global_load_dword v253, v253, s[56:57]
	global_load_dwordx4 v[240:243], v[236:237], off
	global_load_dwordx4 v[244:247], v[236:237], off offset:16
	global_load_dwordx4 v[248:251], v[236:237], off offset:512
	global_load_dwordx2 v[222:223], v[236:237], off offset:528
	s_nop 0
	global_load_dwordx2 v[236:237], v[236:237], off offset:536
	s_add_u32 s4, s44, 0x100
	s_addc_u32 s5, s45, 0
	s_add_i32 s34, 0, 0x10000
	s_cmp_eq_u32 s31, 28
	s_cselect_b32 s43, s95, s5
	s_cselect_b32 s42, s94, s4
	s_cselect_b32 s7, s27, s30
	s_cselect_b32 s6, s28, s29
	s_add_i32 s35, 0, 0x14000
	v_add_u32_e32 v142, s34, v196
	v_add_u32_e32 v158, s35, v196
	ds_read_b128 v[130:133], v142
	ds_read_b128 v[134:137], v142 offset:1024
	ds_read_b128 v[138:141], v142 offset:2048
	ds_read_b128 v[142:145], v142 offset:3072
	ds_read_b128 v[146:149], v158
	ds_read_b128 v[150:153], v158 offset:1024
	ds_read_b128 v[154:157], v158 offset:2048
	ds_read_b128 v[158:161], v158 offset:3072
	v_lshl_add_u64 v[194:195], s[44:45], 0, v[186:187]
	s_add_i32 m0, s93, 0xc000
	ds_read_b128 v[162:165], v201
	ds_read_b128 v[166:169], v201 offset:1024
	ds_read_b128 v[170:173], v201 offset:2048
	ds_read_b128 v[174:177], v201 offset:3072
	ds_read_b128 v[190:193], v201 offset:4096
	ds_read_b128 v[202:205], v201 offset:5120
	ds_read_b128 v[206:209], v201 offset:6144
	ds_read_b128 v[210:213], v201 offset:7168
	global_load_lds_dwordx4 v[194:195], off
	s_add_i32 m0, s93, 0xe000
	v_lshl_add_u64 v[194:195], s[44:45], 0, v[188:189]
	global_load_lds_dwordx4 v[194:195], off
	s_setprio 1
	s_waitcnt lgkmcnt(0)
	s_barrier
	v_mfma_f32_16x16x32_bf16 v[126:129], v[130:133], v[162:165], 0
	v_mfma_f32_16x16x32_bf16 v[122:125], v[138:141], v[162:165], 0
	v_mfma_f32_16x16x32_bf16 v[118:121], v[130:133], v[170:173], 0
	v_mfma_f32_16x16x32_bf16 v[114:117], v[138:141], v[170:173], 0
	v_mfma_f32_16x16x32_bf16 v[110:113], v[130:133], v[190:193], 0
	v_mfma_f32_16x16x32_bf16 v[102:105], v[138:141], v[190:193], 0
	v_mfma_f32_16x16x32_bf16 v[90:93], v[130:133], v[206:209], 0
	v_mfma_f32_16x16x32_bf16 v[82:85], v[138:141], v[206:209], 0
	v_mfma_f32_16x16x32_bf16 v[126:129], v[134:137], v[166:169], v[126:129]
	v_mfma_f32_16x16x32_bf16 v[122:125], v[142:145], v[166:169], v[122:125]
	v_mfma_f32_16x16x32_bf16 v[118:121], v[134:137], v[174:177], v[118:121]
	v_mfma_f32_16x16x32_bf16 v[114:117], v[142:145], v[174:177], v[114:117]
	v_mfma_f32_16x16x32_bf16 v[110:113], v[134:137], v[202:205], v[110:113]
	v_mfma_f32_16x16x32_bf16 v[102:105], v[142:145], v[202:205], v[102:105]
	v_mfma_f32_16x16x32_bf16 v[90:93], v[134:137], v[210:213], v[90:93]
	v_mfma_f32_16x16x32_bf16 v[82:85], v[142:145], v[210:213], v[82:85]
	v_mfma_f32_16x16x32_bf16 v[106:109], v[146:149], v[162:165], 0
	v_mfma_f32_16x16x32_bf16 v[98:101], v[154:157], v[162:165], 0
	v_mfma_f32_16x16x32_bf16 v[94:97], v[146:149], v[170:173], 0
	v_mfma_f32_16x16x32_bf16 v[86:89], v[154:157], v[170:173], 0
	v_mfma_f32_16x16x32_bf16 v[70:73], v[146:149], v[190:193], 0
	v_mfma_f32_16x16x32_bf16 v[62:65], v[154:157], v[190:193], 0
	v_mfma_f32_16x16x32_bf16 v[78:81], v[146:149], v[206:209], 0
	v_mfma_f32_16x16x32_bf16 v[66:69], v[154:157], v[206:209], 0
	v_mfma_f32_16x16x32_bf16 v[106:109], v[150:153], v[166:169], v[106:109]
	v_mfma_f32_16x16x32_bf16 v[98:101], v[158:161], v[166:169], v[98:101]
	v_mfma_f32_16x16x32_bf16 v[94:97], v[150:153], v[174:177], v[94:97]
	v_mfma_f32_16x16x32_bf16 v[86:89], v[158:161], v[174:177], v[86:89]
	v_mfma_f32_16x16x32_bf16 v[70:73], v[150:153], v[202:205], v[70:73]
	v_mfma_f32_16x16x32_bf16 v[62:65], v[158:161], v[202:205], v[62:65]
	v_mfma_f32_16x16x32_bf16 v[78:81], v[150:153], v[210:213], v[78:81]
	v_mfma_f32_16x16x32_bf16 v[66:69], v[158:161], v[210:213], v[66:69]
	s_setprio 0
	s_barrier
; #define PG8_STAGE(bufoff, gbase, voff) do { _Pragma("unroll") for (int _i = 0; _i < 2; ++_i) \
;         __builtin_amdgcn_global_load_lds((const unsigned*)((const char*)(gbase) + (voff)[_i]), (LAS unsigned*)(lds + (bufoff) + ldsw + _i * 8192), 16, 0, 0); } while (0)
; #define PG8_LDA(dst, b, h) do { _Pragma("unroll") for (int m = 0; m < 4; ++m) _Pragma("unroll") for (int k = 0; k < 2; ++k) dst[m][k] = *(const LAS bf16x8*)(lds + PG8_SA(b, h) + aoff + m * 2048 + k * 1024); } while (0)
; #define PG8_LDB(dst, b, h) do { _Pragma("unroll") for (int n = 0; n < 2; ++n) _Pragma("unroll") for (int k = 0; k < 2; ++k) dst[n][k] = *(const LAS bf16x8*)(lds + PG8_SB(b, h) + boff + n * 2048 + k * 1024); } while (0)
; #define PG8_MMA(ai, bj, At, Bt) do { __builtin_amdgcn_s_setprio(1); _Pragma("unroll") for (int m = 0; m < 4; ++m) _Pragma("unroll") for (int n = 0; n < 2; ++n) _Pragma("unroll") for (int k = 0; k < 2; ++k) \
;         acc[ai][bj][m][n] = __builtin_amdgcn_mfma_f32_16x16x32_bf16(Bt[n][k], At[m][k], acc[ai][bj][m][n], 0, 0, 0); __builtin_amdgcn_s_setprio(0); } while (0)
; #define PG8_WAIT_V(n) asm volatile("s_waitcnt vmcnt(" #n ")" ::: "memory")
; #define PG8_WAIT_L(n) asm volatile("s_waitcnt lgkmcnt(" #n ")" ::: "memory")
; #define PG8_BAR __builtin_amdgcn_s_barrier()
; #define PG8_SCHED __builtin_amdgcn_sched_barrier(0)
; template <class Epi, int AMODE>
; __device__ __forceinline__ void gemm_phase(LAS unsigned char* lds, const Gemm g, const StaticOrder& S, const Epi& E, int stagger_us, int tid_in) {
;     ...
;             PG8_WAIT_V(8); PG8_WAIT_L(0); PG8_BAR; PG8_MMA(0, 0, At, B0); PG8_MMA(0, 1, At, B1); PG8_BAR; PG8_SCHED;
;             PG8_LDA(At, 0, 1); PG8_STAGE(PG8_SB(0, 0), b2, voffB); PG8_STAGE(PG8_SB(0, 1), b2 + hstepB, voffB); PG8_STAGE(PG8_SA(0, 0), a2, voffA);
;             PG8_WAIT_V(8); PG8_WAIT_L(0); PG8_BAR; PG8_MMA(1, 0, At, B0); PG8_MMA(1, 1, At, B1); PG8_BAR; PG8_SCHED;
;             PG8_LDB(B0, 1, 0); PG8_LDB(B1, 1, 1); PG8_SCHED; PG8_LDA(At, 1, 0); PG8_STAGE(PG8_SA(0, 1), a2 + hstepA, voffA);
;             PG8_WAIT_V(8); PG8_WAIT_L(0); PG8_BAR; PG8_MMA(0, 0, At, B0); PG8_MMA(0, 1, At, B1); PG8_BAR; PG8_SCHED;
	s_add_i32 s34, s34, s91
	v_lshl_add_u64 v[194:195], s[6:7], 0, v[0:1]
	s_mov_b32 m0, s34
	ds_read_b128 v[162:165], v201 offset:16384
	ds_read_b128 v[166:169], v201 offset:17408
	ds_read_b128 v[170:173], v201 offset:18432
	ds_read_b128 v[174:177], v201 offset:19456
	ds_read_b128 v[190:193], v201 offset:20480
	ds_read_b128 v[202:205], v201 offset:21504
	ds_read_b128 v[206:209], v201 offset:22528
	ds_read_b128 v[210:213], v201 offset:23552
	global_load_lds_dwordx4 v[194:195], off
	s_add_i32 m0, s34, 0x2000
	s_add_u32 s44, s6, 0x80000
	v_lshl_add_u64 v[214:215], s[6:7], 0, v[182:183]
	s_addc_u32 s45, s7, 0
	s_add_i32 s34, s35, s91
	global_load_lds_dwordx4 v[214:215], off
	v_lshl_add_u64 v[216:217], s[44:45], 0, v[0:1]
	s_mov_b32 m0, s34
	v_lshl_add_u64 v[218:219], s[42:43], 0, v[180:181]
	global_load_lds_dwordx4 v[216:217], off
	s_add_i32 m0, s34, 0x2000
	v_lshl_add_u64 v[216:217], s[44:45], 0, v[182:183]
	global_load_lds_dwordx4 v[216:217], off
	s_mov_b32 m0, s93
	v_lshl_add_u64 v[216:217], s[42:43], 0, v[178:179]
	global_load_lds_dwordx4 v[216:217], off
	s_mov_b32 m0, s83
	s_nop 0
	global_load_lds_dwordx4 v[218:219], off
	s_setprio 1
	s_waitcnt lgkmcnt(0)
	s_barrier
	v_mfma_f32_16x16x32_bf16 v[54:57], v[130:133], v[162:165], 0
	v_mfma_f32_16x16x32_bf16 v[46:49], v[138:141], v[162:165], 0
	v_mfma_f32_16x16x32_bf16 v[38:41], v[130:133], v[170:173], 0
	v_mfma_f32_16x16x32_bf16 v[50:53], v[138:141], v[170:173], 0
	v_mfma_f32_16x16x32_bf16 v[18:21], v[130:133], v[190:193], 0
	v_mfma_f32_16x16x32_bf16 v[34:37], v[138:141], v[190:193], 0
	v_mfma_f32_16x16x32_bf16 v[22:25], v[130:133], v[206:209], 0
	v_mfma_f32_16x16x32_bf16 v[74:77], v[138:141], v[206:209], 0
	v_mfma_f32_16x16x32_bf16 v[54:57], v[134:137], v[166:169], v[54:57]
	v_mfma_f32_16x16x32_bf16 v[46:49], v[142:145], v[166:169], v[46:49]
	v_mfma_f32_16x16x32_bf16 v[38:41], v[134:137], v[174:177], v[38:41]
	v_mfma_f32_16x16x32_bf16 v[50:53], v[142:145], v[174:177], v[50:53]
	v_mfma_f32_16x16x32_bf16 v[18:21], v[134:137], v[202:205], v[18:21]
	v_mfma_f32_16x16x32_bf16 v[34:37], v[142:145], v[202:205], v[34:37]
	v_mfma_f32_16x16x32_bf16 v[22:25], v[134:137], v[210:213], v[22:25]
	v_mfma_f32_16x16x32_bf16 v[74:77], v[142:145], v[210:213], v[74:77]
	v_mfma_f32_16x16x32_bf16 v[58:61], v[146:149], v[162:165], 0
	v_mfma_f32_16x16x32_bf16 v[30:33], v[154:157], v[162:165], 0
	v_mfma_f32_16x16x32_bf16 v[42:45], v[146:149], v[170:173], 0
	v_mfma_f32_16x16x32_bf16 v[6:9], v[154:157], v[170:173], 0
	v_mfma_f32_16x16x32_bf16 v[26:29], v[146:149], v[190:193], 0
	v_mfma_f32_16x16x32_bf16 v[10:13], v[154:157], v[190:193], 0
	v_mfma_f32_16x16x32_bf16 v[14:17], v[146:149], v[206:209], 0
	v_mfma_f32_16x16x32_bf16 v[2:5], v[154:157], v[206:209], 0
	v_mfma_f32_16x16x32_bf16 v[58:61], v[150:153], v[166:169], v[58:61]
	v_mfma_f32_16x16x32_bf16 v[30:33], v[158:161], v[166:169], v[30:33]
	v_mfma_f32_16x16x32_bf16 v[42:45], v[150:153], v[174:177], v[42:45]
	v_mfma_f32_16x16x32_bf16 v[6:9], v[158:161], v[174:177], v[6:9]
	v_mfma_f32_16x16x32_bf16 v[26:29], v[150:153], v[202:205], v[26:29]
	v_mfma_f32_16x16x32_bf16 v[10:13], v[158:161], v[202:205], v[10:13]
	v_mfma_f32_16x16x32_bf16 v[14:17], v[150:153], v[210:213], v[14:17]
	v_mfma_f32_16x16x32_bf16 v[2:5], v[158:161], v[210:213], v[2:5]
	s_setprio 0
	s_barrier
	s_add_i32 s34, 0, 0x18000
	s_add_i32 s35, 0, 0x1c000
	v_add_u32_e32 v142, s34, v196
	v_add_u32_e32 v158, s35, v196
	ds_read_b128 v[130:133], v142
	ds_read_b128 v[134:137], v142 offset:1024
	ds_read_b128 v[138:141], v142 offset:2048
	ds_read_b128 v[142:145], v142 offset:3072
	ds_read_b128 v[146:149], v158
	ds_read_b128 v[150:153], v158 offset:1024
	ds_read_b128 v[154:157], v158 offset:2048
	ds_read_b128 v[158:161], v158 offset:3072
	s_add_u32 s42, s42, 0x4000
	s_addc_u32 s43, s43, 0
	s_mov_b32 m0, s79
	v_lshl_add_u64 v[220:221], s[42:43], 0, v[178:179]
	ds_read_b128 v[162:165], v201 offset:32768
	ds_read_b128 v[166:169], v201 offset:33792
	ds_read_b128 v[170:173], v201 offset:34816
	ds_read_b128 v[174:177], v201 offset:35840
	ds_read_b128 v[190:193], v201 offset:36864
	ds_read_b128 v[202:205], v201 offset:37888
	ds_read_b128 v[206:209], v201 offset:38912
	ds_read_b128 v[210:213], v201 offset:39936
	global_load_lds_dwordx4 v[220:221], off
	s_mov_b32 m0, s87
	v_lshl_add_u64 v[220:221], s[42:43], 0, v[180:181]
	global_load_lds_dwordx4 v[220:221], off
	s_setprio 1
	s_waitcnt vmcnt(8) lgkmcnt(0)
	s_barrier
; #define PG8_STAGE(bufoff, gbase, voff) do { _Pragma("unroll") for (int _i = 0; _i < 2; ++_i) \
;         __builtin_amdgcn_global_load_lds((const unsigned*)((const char*)(gbase) + (voff)[_i]), (LAS unsigned*)(lds + (bufoff) + ldsw + _i * 8192), 16, 0, 0); } while (0)
; #define PG8_LDA(dst, b, h) do { _Pragma("unroll") for (int m = 0; m < 4; ++m) _Pragma("unroll") for (int k = 0; k < 2; ++k) dst[m][k] = *(const LAS bf16x8*)(lds + PG8_SA(b, h) + aoff + m * 2048 + k * 1024); } while (0)
; #define PG8_MMA(ai, bj, At, Bt) do { __builtin_amdgcn_s_setprio(1); _Pragma("unroll") for (int m = 0; m < 4; ++m) _Pragma("unroll") for (int n = 0; n < 2; ++n) _Pragma("unroll") for (int k = 0; k < 2; ++k) \
;         acc[ai][bj][m][n] = __builtin_amdgcn_mfma_f32_16x16x32_bf16(Bt[n][k], At[m][k], acc[ai][bj][m][n], 0, 0, 0); __builtin_amdgcn_s_setprio(0); } while (0)
; #define PG8_WAIT_V(n) asm volatile("s_waitcnt vmcnt(" #n ")" ::: "memory")
; #define PG8_WAIT_L(n) asm volatile("s_waitcnt lgkmcnt(" #n ")" ::: "memory")
; #define PG8_BAR __builtin_amdgcn_s_barrier()
; #define PG8_SCHED __builtin_amdgcn_sched_barrier(0)
; template <class Epi, int AMODE>
; __device__ __forceinline__ void gemm_phase(LAS unsigned char* lds, const Gemm g, const StaticOrder& S, const Epi& E, int stagger_us, int tid_in) {
;     ...
;             PG8_WAIT_V(8); PG8_WAIT_L(0); PG8_BAR; PG8_MMA(0, 0, At, B0); PG8_MMA(0, 1, At, B1); PG8_BAR; PG8_SCHED;
;             PG8_LDA(At, 1, 1); PG8_STAGE(PG8_SB(1, 0), b3, voffB); PG8_STAGE(PG8_SB(1, 1), b3 + hstepB, voffB); PG8_STAGE(PG8_SA(1, 0), a3, voffA);
;             PG8_WAIT_V(8); PG8_WAIT_L(0); PG8_BAR; PG8_MMA(1, 0, At, B0); PG8_MMA(1, 1, At, B1); PG8_BAR; PG8_SCHED;
;         }
	v_mfma_f32_16x16x32_bf16 v[126:129], v[130:133], v[162:165], v[126:129]
	v_mfma_f32_16x16x32_bf16 v[122:125], v[138:141], v[162:165], v[122:125]
	v_mfma_f32_16x16x32_bf16 v[118:121], v[130:133], v[170:173], v[118:121]
	v_mfma_f32_16x16x32_bf16 v[114:117], v[138:141], v[170:173], v[114:117]
	v_mfma_f32_16x16x32_bf16 v[110:113], v[130:133], v[190:193], v[110:113]
	v_mfma_f32_16x16x32_bf16 v[102:105], v[138:141], v[190:193], v[102:105]
	v_mfma_f32_16x16x32_bf16 v[90:93], v[130:133], v[206:209], v[90:93]
	v_mfma_f32_16x16x32_bf16 v[82:85], v[138:141], v[206:209], v[82:85]
	v_mfma_f32_16x16x32_bf16 v[126:129], v[134:137], v[166:169], v[126:129]
	v_mfma_f32_16x16x32_bf16 v[122:125], v[142:145], v[166:169], v[122:125]
	v_mfma_f32_16x16x32_bf16 v[118:121], v[134:137], v[174:177], v[118:121]
	v_mfma_f32_16x16x32_bf16 v[114:117], v[142:145], v[174:177], v[114:117]
	v_mfma_f32_16x16x32_bf16 v[110:113], v[134:137], v[202:205], v[110:113]
	v_mfma_f32_16x16x32_bf16 v[102:105], v[142:145], v[202:205], v[102:105]
	v_mfma_f32_16x16x32_bf16 v[90:93], v[134:137], v[210:213], v[90:93]
	v_mfma_f32_16x16x32_bf16 v[82:85], v[142:145], v[210:213], v[82:85]
	v_mfma_f32_16x16x32_bf16 v[106:109], v[146:149], v[162:165], v[106:109]
	v_mfma_f32_16x16x32_bf16 v[98:101], v[154:157], v[162:165], v[98:101]
	v_mfma_f32_16x16x32_bf16 v[94:97], v[146:149], v[170:173], v[94:97]
	v_mfma_f32_16x16x32_bf16 v[86:89], v[154:157], v[170:173], v[86:89]
	v_mfma_f32_16x16x32_bf16 v[70:73], v[146:149], v[190:193], v[70:73]
	v_mfma_f32_16x16x32_bf16 v[62:65], v[154:157], v[190:193], v[62:65]
	v_mfma_f32_16x16x32_bf16 v[78:81], v[146:149], v[206:209], v[78:81]
	v_mfma_f32_16x16x32_bf16 v[66:69], v[154:157], v[206:209], v[66:69]
	v_mfma_f32_16x16x32_bf16 v[106:109], v[150:153], v[166:169], v[106:109]
	v_mfma_f32_16x16x32_bf16 v[98:101], v[158:161], v[166:169], v[98:101]
	v_mfma_f32_16x16x32_bf16 v[94:97], v[150:153], v[174:177], v[94:97]
	v_mfma_f32_16x16x32_bf16 v[86:89], v[158:161], v[174:177], v[86:89]
	v_mfma_f32_16x16x32_bf16 v[70:73], v[150:153], v[202:205], v[70:73]
	v_mfma_f32_16x16x32_bf16 v[62:65], v[158:161], v[202:205], v[62:65]
	v_mfma_f32_16x16x32_bf16 v[78:81], v[150:153], v[210:213], v[78:81]
	v_mfma_f32_16x16x32_bf16 v[66:69], v[158:161], v[210:213], v[66:69]
	s_setprio 0
	s_barrier
	s_add_i32 s34, s34, s91
	v_lshl_add_u64 v[194:195], v[194:195], 0, s[74:75]
	s_mov_b32 m0, s34
	ds_read_b128 v[162:165], v201 offset:49152
	ds_read_b128 v[166:169], v201 offset:50176
	ds_read_b128 v[170:173], v201 offset:51200
	ds_read_b128 v[174:177], v201 offset:52224
	ds_read_b128 v[190:193], v201 offset:53248
	ds_read_b128 v[202:205], v201 offset:54272
	ds_read_b128 v[206:209], v201 offset:55296
	ds_read_b128 v[210:213], v201 offset:56320
	global_load_lds_dwordx4 v[194:195], off
	s_add_i32 m0, s34, 0x2000
	s_add_u32 s6, s6, 0x80080
	v_lshl_add_u64 v[194:195], v[214:215], 0, s[74:75]
	s_addc_u32 s7, s7, 0
	s_add_i32 s34, s35, s91
	global_load_lds_dwordx4 v[194:195], off
	s_mov_b32 m0, s34
	v_lshl_add_u64 v[194:195], s[6:7], 0, v[0:1]
	global_load_lds_dwordx4 v[194:195], off
	s_add_i32 m0, s34, 0x2000
	v_lshl_add_u64 v[194:195], s[6:7], 0, v[182:183]
	global_load_lds_dwordx4 v[194:195], off
	s_mov_b32 m0, s67
	v_lshl_add_u64 v[194:195], v[216:217], 0, s[74:75]
	global_load_lds_dwordx4 v[194:195], off
	s_mov_b32 m0, s85
	v_lshl_add_u64 v[194:195], v[218:219], 0, s[74:75]
	global_load_lds_dwordx4 v[194:195], off
	s_setprio 1
	s_waitcnt vmcnt(8) lgkmcnt(0)
	s_barrier
	v_mfma_f32_16x16x32_bf16 v[54:57], v[130:133], v[162:165], v[54:57]
	v_mfma_f32_16x16x32_bf16 v[46:49], v[138:141], v[162:165], v[46:49]
	v_mfma_f32_16x16x32_bf16 v[38:41], v[130:133], v[170:173], v[38:41]
	v_mfma_f32_16x16x32_bf16 v[50:53], v[138:141], v[170:173], v[50:53]
	v_mfma_f32_16x16x32_bf16 v[18:21], v[130:133], v[190:193], v[18:21]
	v_mfma_f32_16x16x32_bf16 v[34:37], v[138:141], v[190:193], v[34:37]
	v_mfma_f32_16x16x32_bf16 v[22:25], v[130:133], v[206:209], v[22:25]
	v_mfma_f32_16x16x32_bf16 v[74:77], v[138:141], v[206:209], v[74:77]
	v_mfma_f32_16x16x32_bf16 v[54:57], v[134:137], v[166:169], v[54:57]
	v_mfma_f32_16x16x32_bf16 v[46:49], v[142:145], v[166:169], v[46:49]
	v_mfma_f32_16x16x32_bf16 v[38:41], v[134:137], v[174:177], v[38:41]
	v_mfma_f32_16x16x32_bf16 v[50:53], v[142:145], v[174:177], v[50:53]
	v_mfma_f32_16x16x32_bf16 v[18:21], v[134:137], v[202:205], v[18:21]
	v_mfma_f32_16x16x32_bf16 v[34:37], v[142:145], v[202:205], v[34:37]
	v_mfma_f32_16x16x32_bf16 v[22:25], v[134:137], v[210:213], v[22:25]
	v_mfma_f32_16x16x32_bf16 v[74:77], v[142:145], v[210:213], v[74:77]
	v_mfma_f32_16x16x32_bf16 v[58:61], v[146:149], v[162:165], v[58:61]
	v_mfma_f32_16x16x32_bf16 v[30:33], v[154:157], v[162:165], v[30:33]
	v_mfma_f32_16x16x32_bf16 v[42:45], v[146:149], v[170:173], v[42:45]
	v_mfma_f32_16x16x32_bf16 v[6:9], v[154:157], v[170:173], v[6:9]
	v_mfma_f32_16x16x32_bf16 v[26:29], v[146:149], v[190:193], v[26:29]
	v_mfma_f32_16x16x32_bf16 v[10:13], v[154:157], v[190:193], v[10:13]
	v_mfma_f32_16x16x32_bf16 v[14:17], v[146:149], v[206:209], v[14:17]
	v_mfma_f32_16x16x32_bf16 v[2:5], v[154:157], v[206:209], v[2:5]
	v_mfma_f32_16x16x32_bf16 v[58:61], v[150:153], v[166:169], v[58:61]
	v_mfma_f32_16x16x32_bf16 v[30:33], v[158:161], v[166:169], v[30:33]
	v_mfma_f32_16x16x32_bf16 v[42:45], v[150:153], v[174:177], v[42:45]
	v_mfma_f32_16x16x32_bf16 v[6:9], v[158:161], v[174:177], v[6:9]
	v_mfma_f32_16x16x32_bf16 v[26:29], v[150:153], v[202:205], v[26:29]
	v_mfma_f32_16x16x32_bf16 v[10:13], v[158:161], v[202:205], v[10:13]
	v_mfma_f32_16x16x32_bf16 v[14:17], v[150:153], v[210:213], v[14:17]
	v_mfma_f32_16x16x32_bf16 v[2:5], v[158:161], v[210:213], v[2:5]
	s_setprio 0
	s_barrier
	s_add_i32 s31, s31, 2
	s_add_u32 s29, s29, 0x100
	s_addc_u32 s30, s30, 0
	s_cmp_gt_u32 s31, 29
	s_mov_b64 s[44:45], s[4:5]
